# work-queue fetch uses a scalar atomic (s_atomic_add, lgkmcnt) so thread 0 does not wait for its wave's outstanding vector stores
# speedup vs baseline: 1.0088x; 1.0038x over previous
.Lqf_dyn_1:
	s_mov_b32 s98, 1
	s_atomic_add s98, s[8:9], 0x4 glc
	s_waitcnt lgkmcnt(0)
	v_add_u32_e32 v0, s98, v255

.Lqf_dyn_2:
	s_mov_b32 s98, 1
	s_atomic_add s98, s[6:7], 0x8 glc
	s_waitcnt lgkmcnt(0)
	v_add_u32_e32 v0, s98, v255

.Lqf_dyn_3:
	s_mov_b32 s98, 1
	s_atomic_add s98, s[20:21], 0x0 glc
	s_waitcnt lgkmcnt(0)
	v_add_u32_e32 v0, s98, v255

.Lqf_dyn_4:
	s_mov_b32 s98, 1
	s_atomic_add s98, s[26:27], 0xc glc
	s_waitcnt lgkmcnt(0)
	v_add_u32_e32 v0, s98, v255
	v_add_u32_e32 v0, -16, v0
